# natten: V^T row loads of a key row batched (counted vmcnt) on top of v11
# speedup vs baseline: 1.0648x; 1.0015x over previous
; template <bool CL>
; __device__ __forceinline__ void natten_wave(const Params& p, int l, bool local, int b, int hh, int qrow0  ,
;                             int r, int ct, const f16* lK, const f16* lV) {
;     ...
; #pragma unroll
;   for (int cb = 0; cb < 16; ++cb) {
;     const int key = (cb >> 1) * 32 + kperm + 4 * (cb & 1);
;     f16x8 k0, k1;
;     if (CL) {
;       const f16* kp = lK + key * 72 + g * 16;
;       k0 = *(const f16x8*)(kp);
;       k1 = *(const f16x8*)(kp + 8);
;     } else {
;       const f16* kp = proj + (size_t)(NLAT + b * CTXL + key) * PJ + RD + hh * HD + g * 16;
;       k0 = *(const f16x8*)(kp);
;       k1 = *(const f16x8*)(kp + 8);
;     }
;     f32x4 a = f32x4{0.f, 0.f, 0.f, 0.f};
;     a = __builtin_amdgcn_mfma_f32_16x16x32_f16(k0, qf[0], a, 0, 0, 0);
;     a = __builtin_amdgcn_mfma_f32_16x16x32_f16(k1, qf[1], a, 0, 0, 0);
; #pragma unroll
;     for (int i = 0; i < 4; ++i) mx = fmaxf(mx, a[i]);
;     sc[cb] = a;
;     if (CL && (cb & 3) == 3) __builtin_amdgcn_sched_barrier(0);
;   }
;   mx = fmaxf(mx, __shfl_xor(mx, 16, 64));
;   mx = fmaxf(mx, __shfl_xor(mx, 32, 64));
.LBB0_548:
	s_or_b64 exec, exec, s[10:11]
	ds_read_b128 v[4:7], v117
	ds_read_b128 v[8:11], v117 offset:16
	ds_read_b128 v[12:15], v117 offset:576
	ds_read_b128 v[16:19], v117 offset:592
	v_ashrrev_i32_e32 v97, 31, v96
	s_waitcnt lgkmcnt(3)
	v_mfma_f32_16x16x32_f16 v[4:7], v[4:7], v[64:67], 0
	s_waitcnt lgkmcnt(2)
	v_mfma_f32_16x16x32_f16 v[60:63], v[8:11], v[0:3], v[4:7]
	ds_read_b128 v[8:11], v117 offset:4624
	s_nop 4
	ds_read_b128 v[4:7], v117 offset:4608
	s_waitcnt lgkmcnt(3)
	v_mfma_f32_16x16x32_f16 v[12:15], v[12:15], v[64:67], 0
	s_waitcnt lgkmcnt(2)
	v_mfma_f32_16x16x32_f16 v[56:59], v[16:19], v[0:3], v[12:15]
	s_waitcnt lgkmcnt(0)
	v_mfma_f32_16x16x32_f16 v[4:7], v[4:7], v[64:67], 0
	s_nop 3
	ds_read_b128 v[12:15], v117 offset:5184
	v_mfma_f32_16x16x32_f16 v[52:55], v[8:11], v[0:3], v[4:7]
	s_waitcnt lgkmcnt(0)
	v_mfma_f32_16x16x32_f16 v[8:11], v[12:15], v[64:67], 0
	s_nop 0
	ds_read_b128 v[4:7], v117 offset:5200
	s_waitcnt lgkmcnt(0)
	v_mfma_f32_16x16x32_f16 v[48:51], v[4:7], v[0:3], v[8:11]
	ds_read_b128 v[4:7], v117 offset:9216
	s_nop 2
	ds_read_b128 v[8:11], v117 offset:9232
	ds_read_b128 v[12:15], v117 offset:9792
	ds_read_b128 v[16:19], v117 offset:9808
	s_waitcnt lgkmcnt(3)
	v_mfma_f32_16x16x32_f16 v[4:7], v[4:7], v[64:67], 0
	s_waitcnt lgkmcnt(2)
	v_mfma_f32_16x16x32_f16 v[44:47], v[8:11], v[0:3], v[4:7]
	ds_read_b128 v[8:11], v117 offset:13840
	s_nop 4
	ds_read_b128 v[4:7], v117 offset:13824
	s_waitcnt lgkmcnt(3)
	v_mfma_f32_16x16x32_f16 v[12:15], v[12:15], v[64:67], 0
	s_waitcnt lgkmcnt(2)
	v_mfma_f32_16x16x32_f16 v[40:43], v[16:19], v[0:3], v[12:15]
	s_waitcnt lgkmcnt(0)
	v_mfma_f32_16x16x32_f16 v[4:7], v[4:7], v[64:67], 0
	s_nop 3
	ds_read_b128 v[12:15], v117 offset:14400
	v_mfma_f32_16x16x32_f16 v[36:39], v[8:11], v[0:3], v[4:7]
	s_waitcnt lgkmcnt(0)
	v_mfma_f32_16x16x32_f16 v[8:11], v[12:15], v[64:67], 0
	s_nop 0
	ds_read_b128 v[4:7], v117 offset:14416
	s_waitcnt lgkmcnt(0)
	v_mfma_f32_16x16x32_f16 v[32:35], v[4:7], v[0:3], v[8:11]
	ds_read_b128 v[4:7], v117 offset:18432
	s_nop 2
	ds_read_b128 v[8:11], v117 offset:18448
	ds_read_b128 v[12:15], v117 offset:19008
	ds_read_b128 v[16:19], v117 offset:19024
	s_waitcnt lgkmcnt(3)
	v_mfma_f32_16x16x32_f16 v[4:7], v[4:7], v[64:67], 0
	s_waitcnt lgkmcnt(2)
	v_mfma_f32_16x16x32_f16 v[28:31], v[8:11], v[0:3], v[4:7]
	ds_read_b128 v[8:11], v117 offset:23056
	s_nop 4
	ds_read_b128 v[4:7], v117 offset:23040
	s_waitcnt lgkmcnt(3)
	v_mfma_f32_16x16x32_f16 v[12:15], v[12:15], v[64:67], 0
	s_waitcnt lgkmcnt(2)
	v_mfma_f32_16x16x32_f16 v[24:27], v[16:19], v[0:3], v[12:15]
	s_waitcnt lgkmcnt(0)
	v_mfma_f32_16x16x32_f16 v[4:7], v[4:7], v[64:67], 0
	s_nop 3
	ds_read_b128 v[12:15], v117 offset:23616
	v_mfma_f32_16x16x32_f16 v[20:23], v[8:11], v[0:3], v[4:7]
	s_waitcnt lgkmcnt(0)
	v_mfma_f32_16x16x32_f16 v[8:11], v[12:15], v[64:67], 0
	s_nop 0
	ds_read_b128 v[4:7], v117 offset:23632
	s_waitcnt lgkmcnt(0)
	v_mfma_f32_16x16x32_f16 v[16:19], v[4:7], v[0:3], v[8:11]
	ds_read_b128 v[4:7], v117 offset:27648
	ds_read_b128 v[12:15], v117 offset:27664
	s_nop 1
	ds_read_b128 v[8:11], v117 offset:28224
	ds_read_b128 v[192:195], v117 offset:32272
	s_waitcnt lgkmcnt(3)
	v_mfma_f32_16x16x32_f16 v[4:7], v[4:7], v[64:67], 0
	s_waitcnt lgkmcnt(2)
	v_mfma_f32_16x16x32_f16 v[12:15], v[12:15], v[0:3], v[4:7]
	s_nop 5
	ds_read_b128 v[4:7], v117 offset:28240
	s_waitcnt lgkmcnt(2)
	v_mfma_f32_16x16x32_f16 v[8:11], v[8:11], v[64:67], 0
	s_waitcnt lgkmcnt(0)
	v_mfma_f32_16x16x32_f16 v[8:11], v[4:7], v[0:3], v[8:11]
	ds_read_b128 v[4:7], v117 offset:32256
	s_waitcnt lgkmcnt(0)
	v_mfma_f32_16x16x32_f16 v[4:7], v[4:7], v[64:67], 0
	v_mfma_f32_16x16x32_f16 v[4:7], v[192:195], v[0:3], v[4:7]
	ds_read_b128 v[192:195], v117 offset:32832
	s_waitcnt lgkmcnt(0)
	v_mfma_f32_16x16x32_f16 v[64:67], v[192:195], v[64:67], 0
	ds_read_b128 v[192:195], v117 offset:32848
	s_waitcnt lgkmcnt(0)
	v_mfma_f32_16x16x32_f16 v[0:3], v[192:195], v[0:3], v[64:67]
	s_nop 4
	v_max3_f32 v64, v70, s71, v69
	v_max3_f32 v64, v64, v72, v71
	v_max3_f32 v64, v64, v74, v73
	v_max3_f32 v64, v64, v76, v75
	v_max3_f32 v64, v64, v161, v160
	v_max3_f32 v64, v64, v163, v162
	v_max3_f32 v64, v64, v167, v166
	v_max3_f32 v64, v64, v169, v168
	v_max3_f32 v64, v64, v149, v148
	v_max3_f32 v64, v64, v153, v151
	v_max3_f32 v64, v64, v157, v156
	v_max3_f32 v64, v64, v159, v158
	v_max3_f32 v64, v64, v81, v80
	v_max3_f32 v64, v64, v83, v82
	v_max3_f32 v64, v64, v152, v150
	v_max3_f32 v64, v64, v155, v154
	v_max3_f32 v64, v64, v141, v140
	v_max3_f32 v64, v64, v143, v142
	v_max3_f32 v64, v64, v145, v144
	v_max3_f32 v64, v64, v147, v146
	v_max3_f32 v64, v64, v133, v132
	v_max3_f32 v64, v64, v135, v134
	v_max3_f32 v64, v64, v137, v136
	v_max3_f32 v64, v64, v139, v138
	v_max3_f32 v64, v64, v85, v84
	v_max3_f32 v64, v64, v87, v86
	v_max3_f32 v64, v64, v129, v128
	v_max3_f32 v64, v64, v131, v130
	v_max3_f32 v64, v64, v121, v120
	v_max3_f32 v64, v64, v123, v122
	v_max3_f32 v64, v64, v125, v124
	v_max3_f32 v64, v64, v127, v126
	v_max3_f32 v64, v64, v60, v61
	v_max3_f32 v64, v64, v62, v63
	v_max3_f32 v64, v64, v56, v57
	v_max3_f32 v64, v64, v58, v59
	v_max3_f32 v64, v64, v52, v53
	v_max3_f32 v64, v64, v54, v55
	v_max3_f32 v64, v64, v48, v49
	v_max3_f32 v64, v64, v50, v51
	v_max3_f32 v64, v64, v44, v45
	v_max3_f32 v64, v64, v46, v47
	v_max3_f32 v64, v64, v40, v41
	v_max3_f32 v64, v64, v42, v43
	v_max3_f32 v64, v64, v36, v37
	v_max3_f32 v64, v64, v38, v39
	v_max3_f32 v64, v64, v32, v33
	v_max3_f32 v64, v64, v34, v35
	v_max3_f32 v64, v64, v28, v29
	v_max3_f32 v64, v64, v30, v31
	v_max3_f32 v64, v64, v24, v25
	v_max3_f32 v64, v64, v26, v27
	v_max3_f32 v64, v64, v20, v21
	v_max3_f32 v64, v64, v22, v23
	v_max3_f32 v64, v64, v16, v17
	v_max3_f32 v64, v64, v18, v19
	v_max3_f32 v64, v64, v12, v13
	v_max3_f32 v64, v64, v14, v15
	v_max3_f32 v64, v64, v8, v9
	v_max3_f32 v64, v64, v10, v11
	v_max3_f32 v64, v64, v4, v5
	v_max3_f32 v64, v64, v6, v7
	v_max3_f32 v64, v64, v0, v1
	v_max3_f32 v64, v64, v2, v3
	ds_bpermute_b32 v65, v109, v64
	v_add_u32_e32 v164, v107, v68
	v_lshl_add_u64 v[192:193], v[164:165], 1, v[94:95]
	v_mov_b32_e32 v99, v165
	v_mov_b32_e32 v101, v165
	s_waitcnt lgkmcnt(0)
; template <bool CL>
; __device__ __forceinline__ void natten_wave(const Params& p, int l, bool local, int b, int hh, int qrow0  ,
;                             int r, int ct, const f16* lK, const f16* lV) {
;     ...
;   mx = fmaxf(mx, __shfl_xor(mx, 16, 64));
;   mx = fmaxf(mx, __shfl_xor(mx, 32, 64));
;   float sum = 0.f;
;   f32x4 o[4];
; #pragma unroll
;   for (int nb = 0; nb < 4; ++nb) o[nb] = f32x4{0.f, 0.f, 0.f, 0.f};
;   if (local) {
; #pragma unroll
;     for (int kr = 0; kr < 8; ++kr) {
;       f16x8 pf;
; #pragma unroll
;       for (int blk = 0; blk < 2; ++blk)
; #pragma unroll
;         for (int i = 0; i < 4; ++i) {
;           float e = __expf(sl[kr][blk][i] - mx);
;           sum += e;
;           pf[blk * 4 + i] = (f16)e;
;         }
;       int tk = (rs + kr) * GW + col0 + 8 * g;
; #pragma unroll
;       for (int nb = 0; nb < 4; ++nb) {
;         f16x8 vf = *(const f16x8*)(vt + (size_t)(nb * 16 + lq) * TL + tk);
;         o[nb] = __builtin_amdgcn_mfma_f32_16x16x32_f16(vf, pf, o[nb], 0, 0, 0);
;       }
;     }
	v_max_f32_e32 v65, v65, v65
	v_max_f32_e32 v64, v64, v65
	ds_bpermute_b32 v65, v110, v64
	v_mov_b32_e32 v103, v165
	v_mov_b32_e32 v105, v165
	s_waitcnt lgkmcnt(0)
	v_max_f32_e32 v65, v65, v65
	v_max_f32_e32 v119, v64, v65
	v_sub_f32_e32 v64, v70, v119
	v_mul_f32_e32 v64, 0x3fb8aa3b, v64
	v_sub_f32_e32 v66, v69, v119
	v_exp_f32_e32 v64, v64
	v_mul_f32_e32 v66, 0x3fb8aa3b, v66
	v_sub_f32_e32 v67, v72, v119
	v_exp_f32_e32 v66, v66
	v_mul_f32_e32 v67, 0x3fb8aa3b, v67
	v_sub_f32_e32 v69, v71, v119
	v_exp_f32_e32 v67, v67
	v_mul_f32_e32 v69, 0x3fb8aa3b, v69
	v_exp_f32_e32 v69, v69
	v_add_f32_e32 v65, 0, v64
	v_add_f32_e32 v65, v66, v65
	v_add_f32_e32 v65, v67, v65
	v_add_f32_e32 v170, v69, v65
	v_sub_f32_e32 v65, v74, v119
	v_mul_f32_e32 v65, 0x3fb8aa3b, v65
	v_exp_f32_e32 v196, v65
	v_sub_f32_e32 v65, v73, v119
	v_mul_f32_e32 v65, 0x3fb8aa3b, v65
	v_exp_f32_e32 v197, v65
	v_sub_f32_e32 v65, v76, v119
	v_mul_f32_e32 v65, 0x3fb8aa3b, v65
	v_exp_f32_e32 v198, v65
	v_sub_f32_e32 v65, v75, v119
	v_mul_f32_e32 v65, 0x3fb8aa3b, v65
	v_exp_f32_e32 v199, v65
	v_cvt_pk_f16_f32 v76, v64, v66
	v_lshl_add_u64 v[64:65], v[192:193], 0, v[98:99]
	v_cvt_pk_f16_f32 v77, v67, v69
	global_load_dwordx4 v[64:67], v[64:65], off
	v_cvt_pk_f16_f32 v79, v198, v199
	v_cvt_pk_f16_f32 v78, v196, v197
	v_lshl_add_u64 v[72:73], v[192:193], 0, v[102:103]
	global_load_dwordx4 v[72:75], v[72:73], off
	v_sub_f32_e32 v161, v161, v119
	v_mul_f32_e32 v161, 0x3fb8aa3b, v161
	v_add_f32_e32 v164, v196, v170
	v_exp_f32_e32 v170, v161
	v_add_f32_e32 v164, v197, v164
	v_sub_f32_e32 v160, v160, v119
	v_add_f32_e32 v164, v198, v164
	v_mul_f32_e32 v160, 0x3fb8aa3b, v160
	v_sub_f32_e32 v163, v163, v119
	v_add_f32_e32 v164, v199, v164
	v_exp_f32_e32 v160, v160
	v_mul_f32_e32 v163, 0x3fb8aa3b, v163
	v_sub_f32_e32 v162, v162, v119
	v_add_f32_e32 v161, v170, v164
	v_exp_f32_e32 v164, v163
	v_mul_f32_e32 v162, 0x3fb8aa3b, v162
	v_add_f32_e32 v161, v160, v161
	v_cvt_pk_f16_f32 v160, v170, v160
	v_add_f32_e32 v161, v164, v161
	v_sub_f32_e32 v81, v81, v119
	v_mul_f32_e32 v81, 0x3fb8aa3b, v81
	v_sub_f32_e32 v80, v80, v119
	v_mul_f32_e32 v80, 0x3fb8aa3b, v80
	v_sub_f32_e32 v83, v83, v119
	v_exp_f32_e32 v80, v80
	v_mul_f32_e32 v83, 0x3fb8aa3b, v83
	v_sub_f32_e32 v82, v82, v119
	v_mul_f32_e32 v82, 0x3fb8aa3b, v82
	v_sub_f32_e32 v60, v60, v119
	v_mul_f32_e32 v60, 0x3fb8aa3b, v60
	v_sub_f32_e32 v61, v61, v119
	v_exp_f32_e32 v60, v60
	v_mul_f32_e32 v61, 0x3fb8aa3b, v61
	v_sub_f32_e32 v62, v62, v119
	v_exp_f32_e32 v61, v61
	v_mul_f32_e32 v62, 0x3fb8aa3b, v62
	v_sub_f32_e32 v63, v63, v119
	v_exp_f32_e32 v62, v62
	v_mul_f32_e32 v63, 0x3fb8aa3b, v63
	v_exp_f32_e32 v63, v63
	v_sub_f32_e32 v56, v56, v119
	v_mul_f32_e32 v56, 0x3fb8aa3b, v56
	s_waitcnt vmcnt(0)
	v_mfma_f32_16x16x32_f16 v[72:75], v[72:75], v[76:79], 0
	v_mfma_f32_16x16x32_f16 v[68:71], v[64:67], v[76:79], 0
	v_lshl_add_u64 v[64:65], v[192:193], 0, v[100:101]
	v_lshl_add_u64 v[192:193], v[192:193], 0, v[104:105]
	global_load_dwordx4 v[64:67], v[64:65], off
	s_waitcnt vmcnt(0)
	v_mfma_f32_16x16x32_f16 v[64:67], v[64:67], v[76:79], 0
	global_load_dwordx4 v[192:195], v[192:193], off
	s_waitcnt vmcnt(0)
	v_mfma_f32_16x16x32_f16 v[76:79], v[192:195], v[76:79], 0
	v_exp_f32_e32 v192, v162
	s_nop 0
	v_add_f32_e32 v194, v192, v161
	v_sub_f32_e32 v161, v167, v119
	v_mul_f32_e32 v161, 0x3fb8aa3b, v161
	v_exp_f32_e32 v195, v161
	v_sub_f32_e32 v161, v166, v119
	v_mul_f32_e32 v161, 0x3fb8aa3b, v161
	v_exp_f32_e32 v196, v161
	v_sub_f32_e32 v161, v169, v119
	v_mul_f32_e32 v161, 0x3fb8aa3b, v161
	v_exp_f32_e32 v197, v161
	v_sub_f32_e32 v161, v168, v119
	v_mul_f32_e32 v161, 0x3fb8aa3b, v161
	v_exp_f32_e32 v198, v161
	v_cvt_pk_f16_f32 v161, v164, v192
	v_add_u32_e32 v164, s48, v107
	v_lshl_add_u64 v[192:193], v[164:165], 1, v[94:95]
	v_lshl_add_u64 v[166:167], v[192:193], 0, v[98:99]
	global_load_dwordx4 v[166:169], v[166:167], off
	v_lshl_add_u64 v[244:245], v[192:193], 0, v[100:101]
	global_load_dwordx4 v[244:247], v[244:245], off
	v_cvt_pk_f16_f32 v163, v197, v198
	v_cvt_pk_f16_f32 v162, v195, v196
	v_add_u32_e32 v164, s47, v107
	s_waitcnt vmcnt(1)
	v_mfma_f32_16x16x32_f16 v[68:71], v[166:169], v[160:163], v[68:71]
	s_waitcnt vmcnt(0)
	v_mfma_f32_16x16x32_f16 v[166:169], v[244:247], v[160:163], v[64:67]
	s_nop 2
	v_lshl_add_u64 v[64:65], v[192:193], 0, v[102:103]
	global_load_dwordx4 v[64:67], v[64:65], off
	v_lshl_add_u64 v[244:245], v[192:193], 0, v[104:105]
	global_load_dwordx4 v[244:247], v[244:245], off
	s_waitcnt vmcnt(1)
	v_mfma_f32_16x16x32_f16 v[72:75], v[64:67], v[160:163], v[72:75]
	s_waitcnt vmcnt(0)
	v_mfma_f32_16x16x32_f16 v[76:79], v[244:247], v[160:163], v[76:79]
	v_sub_f32_e32 v65, v149, v119
	v_mul_f32_e32 v65, 0x3fb8aa3b, v65
	v_sub_f32_e32 v66, v148, v119
	v_add_f32_e32 v64, v195, v194
	v_exp_f32_e32 v65, v65
	v_mul_f32_e32 v66, 0x3fb8aa3b, v66
	v_sub_f32_e32 v67, v153, v119
	v_add_f32_e32 v64, v196, v64
	v_exp_f32_e32 v66, v66
	v_mul_f32_e32 v67, 0x3fb8aa3b, v67
	v_sub_f32_e32 v148, v151, v119
	v_add_f32_e32 v64, v197, v64
	v_exp_f32_e32 v67, v67
	v_mul_f32_e32 v148, 0x3fb8aa3b, v148
	v_add_f32_e32 v64, v198, v64
	v_exp_f32_e32 v148, v148
	v_add_f32_e32 v64, v65, v64
	v_add_f32_e32 v64, v66, v64
	v_add_f32_e32 v64, v67, v64
	v_add_f32_e32 v151, v148, v64
	v_sub_f32_e32 v64, v157, v119
	v_mul_f32_e32 v64, 0x3fb8aa3b, v64
	v_exp_f32_e32 v153, v64
	v_sub_f32_e32 v64, v156, v119
	v_mul_f32_e32 v64, 0x3fb8aa3b, v64
	v_exp_f32_e32 v170, v64
	v_sub_f32_e32 v64, v159, v119
	v_mul_f32_e32 v64, 0x3fb8aa3b, v64
	v_exp_f32_e32 v192, v64
	v_sub_f32_e32 v64, v158, v119
	v_mul_f32_e32 v64, 0x3fb8aa3b, v64
	v_cvt_pk_f16_f32 v157, v67, v148
	v_lshl_add_u64 v[148:149], v[164:165], 1, v[94:95]
	v_exp_f32_e32 v193, v64
	v_cvt_pk_f16_f32 v156, v65, v66
	v_lshl_add_u64 v[64:65], v[148:149], 0, v[98:99]
	global_load_dwordx4 v[64:67], v[64:65], off
	v_lshl_add_u64 v[160:161], v[148:149], 0, v[102:103]
	global_load_dwordx4 v[160:163], v[160:161], off
	v_cvt_pk_f16_f32 v159, v192, v193
	v_cvt_pk_f16_f32 v158, v153, v170
	v_add_u32_e32 v164, s46, v107
	s_waitcnt vmcnt(1)
; template <bool CL>
; __device__ __forceinline__ void natten_wave(const Params& p, int l, bool local, int b, int hh, int qrow0  ,
;                             int r, int ct, const f16* lK, const f16* lV) {
;     ...
;   if (local) {
; #pragma unroll
;     for (int kr = 0; kr < 8; ++kr) {
;       f16x8 pf;
; #pragma unroll
;       for (int blk = 0; blk < 2; ++blk)
; #pragma unroll
;         for (int i = 0; i < 4; ++i) {
;           float e = __expf(sl[kr][blk][i] - mx);
;           sum += e;
;           pf[blk * 4 + i] = (f16)e;
;         }
;       int tk = (rs + kr) * GW + col0 + 8 * g;
; #pragma unroll
;       for (int nb = 0; nb < 4; ++nb) {
;         f16x8 vf = *(const f16x8*)(vt + (size_t)(nb * 16 + lq) * TL + tk);
;         o[nb] = __builtin_amdgcn_mfma_f32_16x16x32_f16(vf, pf, o[nb], 0, 0, 0);
;       }
;     }
	v_mfma_f32_16x16x32_f16 v[64:67], v[64:67], v[156:159], v[68:71]
	s_nop 2
	v_lshl_add_u64 v[68:69], v[148:149], 0, v[100:101]
	v_lshl_add_u64 v[148:149], v[148:149], 0, v[104:105]
	global_load_dwordx4 v[68:71], v[68:69], off
	s_waitcnt vmcnt(1)
	v_mfma_f32_16x16x32_f16 v[72:75], v[160:163], v[156:159], v[72:75]
	global_load_dwordx4 v[160:163], v[148:149], off
	v_add_f32_e32 v148, v153, v151
	v_exp_f32_e32 v149, v81
	v_add_f32_e32 v148, v170, v148
	v_add_f32_e32 v148, v192, v148
	v_add_f32_e32 v148, v193, v148
	v_add_f32_e32 v81, v149, v148
	v_exp_f32_e32 v148, v83
	v_exp_f32_e32 v151, v82
	v_add_f32_e32 v81, v80, v81
	s_waitcnt vmcnt(1)
	v_mfma_f32_16x16x32_f16 v[68:71], v[68:71], v[156:159], v[166:169]
	v_add_f32_e32 v81, v148, v81
	v_cvt_pk_f16_f32 v80, v149, v80
	s_waitcnt vmcnt(0)
	v_mfma_f32_16x16x32_f16 v[76:79], v[160:163], v[156:159], v[76:79]
	v_add_f32_e32 v156, v151, v81
	v_sub_f32_e32 v81, v152, v119
	v_mul_f32_e32 v81, 0x3fb8aa3b, v81
	v_exp_f32_e32 v157, v81
	v_sub_f32_e32 v81, v150, v119
	v_mul_f32_e32 v81, 0x3fb8aa3b, v81
	v_exp_f32_e32 v158, v81
	v_sub_f32_e32 v81, v155, v119
	v_mul_f32_e32 v81, 0x3fb8aa3b, v81
	v_exp_f32_e32 v155, v81
	v_sub_f32_e32 v81, v154, v119
	v_mul_f32_e32 v81, 0x3fb8aa3b, v81
	v_lshl_add_u64 v[152:153], v[164:165], 1, v[94:95]
	v_exp_f32_e32 v154, v81
	v_cvt_pk_f16_f32 v81, v148, v151
	v_lshl_add_u64 v[148:149], v[152:153], 0, v[98:99]
	global_load_dwordx4 v[148:151], v[148:149], off
	v_lshl_add_u64 v[244:245], v[152:153], 0, v[100:101]
	global_load_dwordx4 v[244:247], v[244:245], off
	v_lshl_add_u64 v[248:249], v[152:153], 0, v[102:103]
	global_load_dwordx4 v[248:251], v[248:249], off
	v_lshl_add_u64 v[252:253], v[152:153], 0, v[104:105]
	global_load_dwordx4 v[252:255], v[252:253], off
	v_cvt_pk_f16_f32 v83, v155, v154
	v_cvt_pk_f16_f32 v82, v157, v158
	v_add_u32_e32 v164, s41, v107
	s_waitcnt vmcnt(3)
	v_mfma_f32_16x16x32_f16 v[64:67], v[148:151], v[80:83], v[64:67]
	s_waitcnt vmcnt(2)
	v_mfma_f32_16x16x32_f16 v[68:71], v[244:247], v[80:83], v[68:71]
	s_waitcnt vmcnt(1)
	v_mfma_f32_16x16x32_f16 v[72:75], v[248:251], v[80:83], v[72:75]
	s_waitcnt vmcnt(0)
	v_mfma_f32_16x16x32_f16 v[76:79], v[252:255], v[80:83], v[76:79]
	v_sub_f32_e32 v81, v141, v119
	v_mul_f32_e32 v81, 0x3fb8aa3b, v81
	v_exp_f32_e32 v141, v81
	v_sub_f32_e32 v81, v140, v119
	v_mul_f32_e32 v81, 0x3fb8aa3b, v81
	v_add_f32_e32 v80, v157, v156
	v_exp_f32_e32 v140, v81
	v_sub_f32_e32 v81, v143, v119
	v_add_f32_e32 v80, v158, v80
	v_mul_f32_e32 v81, 0x3fb8aa3b, v81
	v_sub_f32_e32 v82, v142, v119
	v_add_f32_e32 v80, v155, v80
	v_exp_f32_e32 v81, v81
	v_mul_f32_e32 v82, 0x3fb8aa3b, v82
	v_add_f32_e32 v80, v154, v80
	v_exp_f32_e32 v142, v82
	v_add_f32_e32 v80, v141, v80
	v_add_f32_e32 v80, v140, v80
	v_add_f32_e32 v80, v81, v80
	v_add_f32_e32 v148, v142, v80
	v_sub_f32_e32 v80, v145, v119
	v_mul_f32_e32 v80, 0x3fb8aa3b, v80
	v_exp_f32_e32 v149, v80
	v_sub_f32_e32 v80, v144, v119
	v_mul_f32_e32 v80, 0x3fb8aa3b, v80
	v_exp_f32_e32 v150, v80
	v_sub_f32_e32 v80, v147, v119
	v_mul_f32_e32 v80, 0x3fb8aa3b, v80
	v_exp_f32_e32 v147, v80
	v_sub_f32_e32 v80, v146, v119
	v_mul_f32_e32 v80, 0x3fb8aa3b, v80
	v_lshl_add_u64 v[144:145], v[164:165], 1, v[94:95]
	v_exp_f32_e32 v146, v80
	v_cvt_pk_f16_f32 v80, v141, v140
	v_lshl_add_u64 v[140:141], v[144:145], 0, v[98:99]
	v_cvt_pk_f16_f32 v81, v81, v142
	global_load_dwordx4 v[140:143], v[140:141], off
	v_lshl_add_u64 v[244:245], v[144:145], 0, v[100:101]
	global_load_dwordx4 v[244:247], v[244:245], off
	v_lshl_add_u64 v[248:249], v[144:145], 0, v[102:103]
	global_load_dwordx4 v[248:251], v[248:249], off
	v_lshl_add_u64 v[252:253], v[144:145], 0, v[104:105]
	global_load_dwordx4 v[252:255], v[252:253], off
	v_cvt_pk_f16_f32 v83, v147, v146
	v_cvt_pk_f16_f32 v82, v149, v150
	v_add_u32_e32 v164, s45, v107
	s_waitcnt vmcnt(3)
	v_mfma_f32_16x16x32_f16 v[64:67], v[140:143], v[80:83], v[64:67]
	s_waitcnt vmcnt(2)
	v_mfma_f32_16x16x32_f16 v[68:71], v[244:247], v[80:83], v[68:71]
	s_waitcnt vmcnt(1)
	v_mfma_f32_16x16x32_f16 v[72:75], v[248:251], v[80:83], v[72:75]
	s_waitcnt vmcnt(0)
	v_mfma_f32_16x16x32_f16 v[76:79], v[252:255], v[80:83], v[76:79]
	v_sub_f32_e32 v81, v133, v119
	v_mul_f32_e32 v81, 0x3fb8aa3b, v81
	v_exp_f32_e32 v133, v81
	v_sub_f32_e32 v81, v132, v119
	v_mul_f32_e32 v81, 0x3fb8aa3b, v81
	v_add_f32_e32 v80, v149, v148
	v_exp_f32_e32 v132, v81
	v_sub_f32_e32 v81, v135, v119
	v_add_f32_e32 v80, v150, v80
	v_mul_f32_e32 v81, 0x3fb8aa3b, v81
	v_sub_f32_e32 v82, v134, v119
	v_add_f32_e32 v80, v147, v80
	v_exp_f32_e32 v81, v81
	v_mul_f32_e32 v82, 0x3fb8aa3b, v82
	v_add_f32_e32 v80, v146, v80
	v_exp_f32_e32 v134, v82
	v_add_f32_e32 v80, v133, v80
	v_add_f32_e32 v80, v132, v80
	v_add_f32_e32 v80, v81, v80
	v_add_f32_e32 v140, v134, v80
	v_sub_f32_e32 v80, v137, v119
	v_mul_f32_e32 v80, 0x3fb8aa3b, v80
	v_exp_f32_e32 v141, v80
	v_sub_f32_e32 v80, v136, v119
	v_mul_f32_e32 v80, 0x3fb8aa3b, v80
	v_exp_f32_e32 v142, v80
	v_sub_f32_e32 v80, v139, v119
	v_mul_f32_e32 v80, 0x3fb8aa3b, v80
	v_exp_f32_e32 v139, v80
	v_sub_f32_e32 v80, v138, v119
	v_mul_f32_e32 v80, 0x3fb8aa3b, v80
	v_lshl_add_u64 v[136:137], v[164:165], 1, v[94:95]
	v_exp_f32_e32 v138, v80
	v_cvt_pk_f16_f32 v80, v133, v132
	v_lshl_add_u64 v[132:133], v[136:137], 0, v[98:99]
	v_cvt_pk_f16_f32 v81, v81, v134
	global_load_dwordx4 v[132:135], v[132:133], off
	v_lshl_add_u64 v[244:245], v[136:137], 0, v[100:101]
	global_load_dwordx4 v[244:247], v[244:245], off
	v_lshl_add_u64 v[248:249], v[136:137], 0, v[102:103]
	global_load_dwordx4 v[248:251], v[248:249], off
	v_lshl_add_u64 v[252:253], v[136:137], 0, v[104:105]
	global_load_dwordx4 v[252:255], v[252:253], off
	v_cvt_pk_f16_f32 v83, v139, v138
	v_cvt_pk_f16_f32 v82, v141, v142
	v_add_u32_e32 v164, s44, v107
	s_waitcnt vmcnt(3)
; template <bool CL>
; __device__ __forceinline__ void natten_wave(const Params& p, int l, bool local, int b, int hh, int qrow0  ,
;                             int r, int ct, const f16* lK, const f16* lV) {
;     ...
;   if (local) {
; #pragma unroll
;     for (int kr = 0; kr < 8; ++kr) {
;       f16x8 pf;
; #pragma unroll
;       for (int blk = 0; blk < 2; ++blk)
; #pragma unroll
;         for (int i = 0; i < 4; ++i) {
;           float e = __expf(sl[kr][blk][i] - mx);
;           sum += e;
;           pf[blk * 4 + i] = (f16)e;
;         }
;       int tk = (rs + kr) * GW + col0 + 8 * g;
; #pragma unroll
;       for (int nb = 0; nb < 4; ++nb) {
;         f16x8 vf = *(const f16x8*)(vt + (size_t)(nb * 16 + lq) * TL + tk);
;         o[nb] = __builtin_amdgcn_mfma_f32_16x16x32_f16(vf, pf, o[nb], 0, 0, 0);
;       }
;     }
;   }
; #pragma unroll
;   for (int pr = 0; pr < 8; ++pr) {
;     f16x8 pf;
; #pragma unroll
;     for (int blk = 0; blk < 2; ++blk)
; #pragma unroll
;       for (int i = 0; i < 4; ++i) {
;         float e = __expf(sc[pr * 2 + blk][i] - mx);
;         sum += e;
;         pf[blk * 4 + i] = (f16)e;
;       }
;     int tk = pr * 32 + 8 * g;
; #pragma unroll
;     for (int nb = 0; nb < 4; ++nb) {
;       f16x8 vf;
;       if (CL) vf = *(const f16x8*)(lV + (nb * 16 + lq) * 264 + tk);
;       else vf = *(const f16x8*)(vtc + (size_t)(nb * 16 + lq) * CTXL + tk);
;       o[nb] = __builtin_amdgcn_mfma_f32_16x16x32_f16(vf, pf, o[nb], 0, 0, 0);
;     }
	v_mfma_f32_16x16x32_f16 v[64:67], v[132:135], v[80:83], v[64:67]
	s_waitcnt vmcnt(2)
	v_mfma_f32_16x16x32_f16 v[68:71], v[244:247], v[80:83], v[68:71]
	s_waitcnt vmcnt(1)
	v_mfma_f32_16x16x32_f16 v[72:75], v[248:251], v[80:83], v[72:75]
	s_waitcnt vmcnt(0)
	v_mfma_f32_16x16x32_f16 v[76:79], v[252:255], v[80:83], v[76:79]
	v_sub_f32_e32 v81, v85, v119
	v_mul_f32_e32 v81, 0x3fb8aa3b, v81
	v_sub_f32_e32 v82, v84, v119
	v_add_f32_e32 v80, v141, v140
	v_exp_f32_e32 v81, v81
	v_mul_f32_e32 v82, 0x3fb8aa3b, v82
	v_sub_f32_e32 v83, v87, v119
	v_add_f32_e32 v80, v142, v80
	v_exp_f32_e32 v82, v82
	v_mul_f32_e32 v83, 0x3fb8aa3b, v83
	v_sub_f32_e32 v84, v86, v119
	v_add_f32_e32 v80, v139, v80
	v_exp_f32_e32 v83, v83
	v_mul_f32_e32 v84, 0x3fb8aa3b, v84
	v_add_f32_e32 v80, v138, v80
	v_exp_f32_e32 v84, v84
	v_add_f32_e32 v80, v81, v80
	v_add_f32_e32 v80, v82, v80
	v_add_f32_e32 v80, v83, v80
	v_add_f32_e32 v134, v84, v80
	v_sub_f32_e32 v80, v129, v119
	v_mul_f32_e32 v80, 0x3fb8aa3b, v80
	v_exp_f32_e32 v135, v80
	v_sub_f32_e32 v80, v128, v119
	v_mul_f32_e32 v80, 0x3fb8aa3b, v80
	v_exp_f32_e32 v136, v80
	v_sub_f32_e32 v80, v131, v119
	v_mul_f32_e32 v80, 0x3fb8aa3b, v80
	v_exp_f32_e32 v137, v80
	v_sub_f32_e32 v80, v130, v119
	v_mul_f32_e32 v80, 0x3fb8aa3b, v80
	v_lshl_add_u64 v[132:133], v[164:165], 1, v[94:95]
	v_exp_f32_e32 v138, v80
	v_cvt_pk_f16_f32 v128, v81, v82
	v_lshl_add_u64 v[80:81], v[132:133], 0, v[98:99]
	v_cvt_pk_f16_f32 v129, v83, v84
	global_load_dwordx4 v[80:83], v[80:81], off
	v_cvt_pk_f16_f32 v131, v137, v138
	v_cvt_pk_f16_f32 v130, v135, v136
	v_add_u32_e32 v164, s42, v107
	s_waitcnt vmcnt(0)
	v_mfma_f32_16x16x32_f16 v[80:83], v[80:83], v[128:131], v[64:67]
	s_nop 2
	v_lshl_add_u64 v[64:65], v[132:133], 0, v[100:101]
	global_load_dwordx4 v[64:67], v[64:65], off
	s_waitcnt vmcnt(0)
	v_mfma_f32_16x16x32_f16 v[84:87], v[64:67], v[128:131], v[68:71]
	v_lshl_add_u64 v[64:65], v[132:133], 0, v[102:103]
	global_load_dwordx4 v[64:67], v[64:65], off
	s_nop 0
	v_sub_f32_e32 v69, v121, v119
	s_waitcnt vmcnt(0)
	v_mfma_f32_16x16x32_f16 v[72:75], v[64:67], v[128:131], v[72:75]
	v_lshl_add_u64 v[64:65], v[132:133], 0, v[104:105]
	global_load_dwordx4 v[64:67], v[64:65], off
	v_mul_f32_e32 v69, 0x3fb8aa3b, v69
	s_waitcnt vmcnt(0)
	v_mfma_f32_16x16x32_f16 v[64:67], v[64:67], v[128:131], v[76:79]
	s_nop 2
	v_exp_f32_e32 v76, v69
	v_sub_f32_e32 v69, v120, v119
	v_mul_f32_e32 v69, 0x3fb8aa3b, v69
	v_add_f32_e32 v68, v135, v134
	v_exp_f32_e32 v77, v69
	v_sub_f32_e32 v69, v123, v119
	v_add_f32_e32 v68, v136, v68
	v_mul_f32_e32 v69, 0x3fb8aa3b, v69
	v_sub_f32_e32 v70, v122, v119
	v_add_f32_e32 v68, v137, v68
	v_exp_f32_e32 v69, v69
	v_mul_f32_e32 v70, 0x3fb8aa3b, v70
	v_add_f32_e32 v68, v138, v68
	v_exp_f32_e32 v78, v70
	v_add_f32_e32 v68, v76, v68
	v_add_f32_e32 v68, v77, v68
	v_add_f32_e32 v68, v69, v68
	v_add_f32_e32 v122, v78, v68
	v_sub_f32_e32 v68, v125, v119
	v_mul_f32_e32 v68, 0x3fb8aa3b, v68
	v_exp_f32_e32 v123, v68
	v_sub_f32_e32 v68, v124, v119
	v_mul_f32_e32 v68, 0x3fb8aa3b, v68
	v_exp_f32_e32 v124, v68
	v_sub_f32_e32 v68, v127, v119
	v_mul_f32_e32 v68, 0x3fb8aa3b, v68
	v_exp_f32_e32 v125, v68
	v_sub_f32_e32 v68, v126, v119
	v_mul_f32_e32 v68, 0x3fb8aa3b, v68
	v_lshl_add_u64 v[120:121], v[164:165], 1, v[94:95]
	v_exp_f32_e32 v126, v68
	v_cvt_pk_f16_f32 v68, v76, v77
	v_lshl_add_u64 v[76:77], v[120:121], 0, v[98:99]
	v_cvt_pk_f16_f32 v69, v69, v78
	global_load_dwordx4 v[76:79], v[76:77], off
	v_cvt_pk_f16_f32 v71, v125, v126
	v_cvt_pk_f16_f32 v70, v123, v124
	s_waitcnt vmcnt(0)
	s_nop 0
	v_mfma_f32_16x16x32_f16 v[80:83], v[76:79], v[68:71], v[80:83]
	v_lshl_add_u64 v[76:77], v[120:121], 0, v[100:101]
	global_load_dwordx4 v[76:79], v[76:77], off
	s_waitcnt vmcnt(0)
	v_mfma_f32_16x16x32_f16 v[76:79], v[76:79], v[68:71], v[84:87]
	s_nop 2
	v_lshl_add_u64 v[84:85], v[120:121], 0, v[102:103]
	global_load_dwordx4 v[84:87], v[84:85], off
	v_lshl_add_u64 v[244:245], v[120:121], 0, v[104:105]
	global_load_dwordx4 v[244:247], v[244:245], off
	s_waitcnt vmcnt(1)
	v_mfma_f32_16x16x32_f16 v[72:75], v[84:87], v[68:71], v[72:75]
	s_waitcnt vmcnt(0)
	v_mfma_f32_16x16x32_f16 v[64:67], v[244:247], v[68:71], v[64:67]
	v_add_f32_e32 v68, v123, v122
	v_add_f32_e32 v68, v124, v68
	v_add_f32_e32 v68, v125, v68
	v_add_f32_e32 v68, v126, v68
	v_add_f32_e32 v68, v60, v68
	v_add_f32_e32 v68, v61, v68
	v_exp_f32_e32 v85, v56
	v_sub_f32_e32 v56, v57, v119
	v_add_f32_e32 v68, v62, v68
	v_mul_f32_e32 v56, 0x3fb8aa3b, v56
	v_add_f32_e32 v84, v63, v68
	v_exp_f32_e32 v86, v56
	v_sub_f32_e32 v56, v58, v119
	ds_read_b128 v[68:71], v118 offset:45312
	v_mul_f32_e32 v56, 0x3fb8aa3b, v56
	v_exp_f32_e32 v87, v56
	v_sub_f32_e32 v56, v59, v119
	v_mul_f32_e32 v56, 0x3fb8aa3b, v56
	v_exp_f32_e32 v99, v56
	v_cvt_pk_f16_f32 v58, v85, v86
	v_cvt_pk_f16_f32 v57, v62, v63
	v_cvt_pk_f16_f32 v56, v60, v61
	v_cvt_pk_f16_f32 v59, v87, v99
	ds_read_b128 v[60:63], v118 offset:36864
	s_waitcnt lgkmcnt(1)
	v_mfma_f32_16x16x32_f16 v[68:71], v[68:71], v[56:59], v[76:79]
	s_nop 2
	ds_read_b128 v[76:79], v118 offset:53760
	s_waitcnt lgkmcnt(0)
	v_mfma_f32_16x16x32_f16 v[72:75], v[76:79], v[56:59], v[72:75]
	ds_read_b128 v[76:79], v118 offset:62208
	v_mfma_f32_16x16x32_f16 v[60:63], v[60:63], v[56:59], v[80:83]
	s_waitcnt lgkmcnt(0)
; template <bool CL>
; __device__ __forceinline__ void natten_wave(const Params& p, int l, bool local, int b, int hh, int qrow0  ,
;                             int r, int ct, const f16* lK, const f16* lV) {
;     ...
; #pragma unroll
;   for (int pr = 0; pr < 8; ++pr) {
;     f16x8 pf;
; #pragma unroll
;     for (int blk = 0; blk < 2; ++blk)
; #pragma unroll
;       for (int i = 0; i < 4; ++i) {
;         float e = __expf(sc[pr * 2 + blk][i] - mx);
;         sum += e;
;         pf[blk * 4 + i] = (f16)e;
;       }
;     int tk = pr * 32 + 8 * g;
; #pragma unroll
;     for (int nb = 0; nb < 4; ++nb) {
;       f16x8 vf;
;       if (CL) vf = *(const f16x8*)(lV + (nb * 16 + lq) * 264 + tk);
;       else vf = *(const f16x8*)(vtc + (size_t)(nb * 16 + lq) * CTXL + tk);
;       o[nb] = __builtin_amdgcn_mfma_f32_16x16x32_f16(vf, pf, o[nb], 0, 0, 0);
;     }
;     if (CL) __builtin_amdgcn_sched_barrier(0);
;   }
	v_mfma_f32_16x16x32_f16 v[56:59], v[76:79], v[56:59], v[64:67]
	s_nop 2
	v_add_f32_e32 v64, v85, v84
	v_add_f32_e32 v64, v86, v64
	v_add_f32_e32 v64, v87, v64
	v_add_f32_e32 v64, v99, v64
	v_sub_f32_e32 v52, v52, v119
	v_mul_f32_e32 v52, 0x3fb8aa3b, v52
	v_sub_f32_e32 v53, v53, v119
	v_sub_f32_e32 v48, v48, v119
	v_exp_f32_e32 v52, v52
	v_mul_f32_e32 v53, 0x3fb8aa3b, v53
	v_sub_f32_e32 v54, v54, v119
	v_mul_f32_e32 v48, 0x3fb8aa3b, v48
	v_exp_f32_e32 v53, v53
	v_mul_f32_e32 v54, 0x3fb8aa3b, v54
	v_sub_f32_e32 v55, v55, v119
	v_exp_f32_e32 v77, v48
	v_sub_f32_e32 v48, v49, v119
	v_exp_f32_e32 v54, v54
	v_mul_f32_e32 v55, 0x3fb8aa3b, v55
	v_mul_f32_e32 v48, 0x3fb8aa3b, v48
	v_exp_f32_e32 v55, v55
	v_exp_f32_e32 v78, v48
	v_sub_f32_e32 v48, v50, v119
	v_add_f32_e32 v64, v52, v64
	v_mul_f32_e32 v48, 0x3fb8aa3b, v48
	v_add_f32_e32 v64, v53, v64
	v_exp_f32_e32 v79, v48
	v_sub_f32_e32 v48, v51, v119
	v_add_f32_e32 v64, v54, v64
	v_mul_f32_e32 v48, 0x3fb8aa3b, v48
	v_add_f32_e32 v76, v55, v64
	v_exp_f32_e32 v80, v48
	v_cvt_pk_f16_f32 v49, v54, v55
	v_cvt_pk_f16_f32 v48, v52, v53
	ds_read_b128 v[52:55], v118 offset:36928
	v_cvt_pk_f16_f32 v51, v79, v80
	v_cvt_pk_f16_f32 v50, v77, v78
	ds_read_b128 v[64:67], v118 offset:53824
	s_waitcnt lgkmcnt(1)
	v_mfma_f32_16x16x32_f16 v[52:55], v[52:55], v[48:51], v[60:63]
	s_nop 2
	ds_read_b128 v[60:63], v118 offset:45376
	s_waitcnt lgkmcnt(0)
	v_mfma_f32_16x16x32_f16 v[60:63], v[60:63], v[48:51], v[68:71]
	s_nop 2
	ds_read_b128 v[68:71], v118 offset:62272
	v_mfma_f32_16x16x32_f16 v[64:67], v[64:67], v[48:51], v[72:75]
	s_waitcnt lgkmcnt(0)
	v_mfma_f32_16x16x32_f16 v[48:51], v[68:71], v[48:51], v[56:59]
	s_nop 2
	v_add_f32_e32 v56, v77, v76
	v_add_f32_e32 v56, v78, v56
	v_add_f32_e32 v56, v79, v56
	v_add_f32_e32 v56, v80, v56
	v_sub_f32_e32 v44, v44, v119
	v_mul_f32_e32 v44, 0x3fb8aa3b, v44
	v_sub_f32_e32 v45, v45, v119
	v_sub_f32_e32 v40, v40, v119
	v_exp_f32_e32 v44, v44
	v_mul_f32_e32 v45, 0x3fb8aa3b, v45
	v_sub_f32_e32 v46, v46, v119
	v_mul_f32_e32 v40, 0x3fb8aa3b, v40
	v_exp_f32_e32 v45, v45
	v_mul_f32_e32 v46, 0x3fb8aa3b, v46
	v_sub_f32_e32 v47, v47, v119
	v_exp_f32_e32 v69, v40
	v_sub_f32_e32 v40, v41, v119
	v_exp_f32_e32 v46, v46
	v_mul_f32_e32 v47, 0x3fb8aa3b, v47
	v_mul_f32_e32 v40, 0x3fb8aa3b, v40
	v_exp_f32_e32 v47, v47
	v_exp_f32_e32 v70, v40
	v_sub_f32_e32 v40, v42, v119
	v_add_f32_e32 v56, v44, v56
	v_mul_f32_e32 v40, 0x3fb8aa3b, v40
	v_add_f32_e32 v56, v45, v56
	v_exp_f32_e32 v71, v40
	v_sub_f32_e32 v40, v43, v119
	v_add_f32_e32 v56, v46, v56
	v_mul_f32_e32 v40, 0x3fb8aa3b, v40
	v_add_f32_e32 v68, v47, v56
	v_exp_f32_e32 v72, v40
	v_cvt_pk_f16_f32 v41, v46, v47
	v_cvt_pk_f16_f32 v40, v44, v45
	ds_read_b128 v[44:47], v118 offset:36992
	v_cvt_pk_f16_f32 v43, v71, v72
	v_cvt_pk_f16_f32 v42, v69, v70
	ds_read_b128 v[56:59], v118 offset:53888
	s_waitcnt lgkmcnt(1)
	v_mfma_f32_16x16x32_f16 v[44:47], v[44:47], v[40:43], v[52:55]
	s_nop 2
	ds_read_b128 v[52:55], v118 offset:45440
	s_waitcnt lgkmcnt(0)
	v_mfma_f32_16x16x32_f16 v[52:55], v[52:55], v[40:43], v[60:63]
	s_nop 2
	ds_read_b128 v[60:63], v118 offset:62336
	v_mfma_f32_16x16x32_f16 v[56:59], v[56:59], v[40:43], v[64:67]
	s_waitcnt lgkmcnt(0)
	v_mfma_f32_16x16x32_f16 v[40:43], v[60:63], v[40:43], v[48:51]
	s_nop 2
	v_add_f32_e32 v48, v69, v68
	v_add_f32_e32 v48, v70, v48
	v_add_f32_e32 v48, v71, v48
	v_add_f32_e32 v48, v72, v48
	v_sub_f32_e32 v36, v36, v119
	v_mul_f32_e32 v36, 0x3fb8aa3b, v36
	v_sub_f32_e32 v37, v37, v119
	v_sub_f32_e32 v32, v32, v119
	v_exp_f32_e32 v36, v36
	v_mul_f32_e32 v37, 0x3fb8aa3b, v37
	v_sub_f32_e32 v38, v38, v119
	v_mul_f32_e32 v32, 0x3fb8aa3b, v32
	v_exp_f32_e32 v37, v37
	v_mul_f32_e32 v38, 0x3fb8aa3b, v38
	v_sub_f32_e32 v39, v39, v119
	v_exp_f32_e32 v61, v32
	v_sub_f32_e32 v32, v33, v119
	v_exp_f32_e32 v38, v38
	v_mul_f32_e32 v39, 0x3fb8aa3b, v39
	v_mul_f32_e32 v32, 0x3fb8aa3b, v32
	v_exp_f32_e32 v39, v39
	v_exp_f32_e32 v62, v32
	v_sub_f32_e32 v32, v34, v119
	v_add_f32_e32 v48, v36, v48
	v_mul_f32_e32 v32, 0x3fb8aa3b, v32
	v_add_f32_e32 v48, v37, v48
	v_exp_f32_e32 v63, v32
	v_sub_f32_e32 v32, v35, v119
	v_add_f32_e32 v48, v38, v48
	v_mul_f32_e32 v32, 0x3fb8aa3b, v32
	v_add_f32_e32 v60, v39, v48
	v_exp_f32_e32 v64, v32
	v_cvt_pk_f16_f32 v33, v38, v39
	v_cvt_pk_f16_f32 v32, v36, v37
	ds_read_b128 v[36:39], v118 offset:37056
	v_cvt_pk_f16_f32 v35, v63, v64
	v_cvt_pk_f16_f32 v34, v61, v62
	ds_read_b128 v[48:51], v118 offset:53952
	s_waitcnt lgkmcnt(1)
	v_mfma_f32_16x16x32_f16 v[36:39], v[36:39], v[32:35], v[44:47]
	s_nop 2
	ds_read_b128 v[44:47], v118 offset:45504
	s_waitcnt lgkmcnt(0)
	v_mfma_f32_16x16x32_f16 v[44:47], v[44:47], v[32:35], v[52:55]
	s_nop 2
	ds_read_b128 v[52:55], v118 offset:62400
	v_mfma_f32_16x16x32_f16 v[48:51], v[48:51], v[32:35], v[56:59]
	s_waitcnt lgkmcnt(0)
	v_mfma_f32_16x16x32_f16 v[32:35], v[52:55], v[32:35], v[40:43]
	s_nop 2
	v_add_f32_e32 v40, v61, v60
	v_add_f32_e32 v40, v62, v40
	v_add_f32_e32 v40, v63, v40
	v_add_f32_e32 v40, v64, v40
	v_sub_f32_e32 v28, v28, v119
	v_mul_f32_e32 v28, 0x3fb8aa3b, v28
	v_sub_f32_e32 v29, v29, v119
	v_sub_f32_e32 v24, v24, v119
	v_exp_f32_e32 v28, v28
	v_mul_f32_e32 v29, 0x3fb8aa3b, v29
	v_sub_f32_e32 v30, v30, v119
	v_mul_f32_e32 v24, 0x3fb8aa3b, v24
	v_exp_f32_e32 v29, v29
	v_mul_f32_e32 v30, 0x3fb8aa3b, v30
	v_sub_f32_e32 v31, v31, v119
	v_exp_f32_e32 v53, v24
	v_sub_f32_e32 v24, v25, v119
	v_exp_f32_e32 v30, v30
	v_mul_f32_e32 v31, 0x3fb8aa3b, v31
	v_mul_f32_e32 v24, 0x3fb8aa3b, v24
	v_exp_f32_e32 v31, v31
	v_exp_f32_e32 v54, v24
	v_sub_f32_e32 v24, v26, v119
	v_add_f32_e32 v40, v28, v40
	v_mul_f32_e32 v24, 0x3fb8aa3b, v24
	v_add_f32_e32 v40, v29, v40
	v_exp_f32_e32 v55, v24
	v_sub_f32_e32 v24, v27, v119
	v_add_f32_e32 v40, v30, v40
	v_mul_f32_e32 v24, 0x3fb8aa3b, v24
	v_add_f32_e32 v52, v31, v40
	v_exp_f32_e32 v56, v24
	v_cvt_pk_f16_f32 v25, v30, v31
	v_cvt_pk_f16_f32 v24, v28, v29
	ds_read_b128 v[28:31], v118 offset:37120
	v_cvt_pk_f16_f32 v27, v55, v56
	v_cvt_pk_f16_f32 v26, v53, v54
	ds_read_b128 v[40:43], v118 offset:54016
	s_waitcnt lgkmcnt(1)
; template <bool CL>
; __device__ __forceinline__ void natten_wave(const Params& p, int l, bool local, int b, int hh, int qrow0  ,
;                             int r, int ct, const f16* lK, const f16* lV) {
;     ...
; #pragma unroll
;   for (int pr = 0; pr < 8; ++pr) {
;     f16x8 pf;
; #pragma unroll
;     for (int blk = 0; blk < 2; ++blk)
; #pragma unroll
;       for (int i = 0; i < 4; ++i) {
;         float e = __expf(sc[pr * 2 + blk][i] - mx);
;         sum += e;
;         pf[blk * 4 + i] = (f16)e;
;       }
;     int tk = pr * 32 + 8 * g;
; #pragma unroll
;     for (int nb = 0; nb < 4; ++nb) {
;       f16x8 vf;
;       if (CL) vf = *(const f16x8*)(lV + (nb * 16 + lq) * 264 + tk);
;       else vf = *(const f16x8*)(vtc + (size_t)(nb * 16 + lq) * CTXL + tk);
;       o[nb] = __builtin_amdgcn_mfma_f32_16x16x32_f16(vf, pf, o[nb], 0, 0, 0);
;     }
;     if (CL) __builtin_amdgcn_sched_barrier(0);
;   }
	v_mfma_f32_16x16x32_f16 v[28:31], v[28:31], v[24:27], v[36:39]
	s_nop 2
	ds_read_b128 v[36:39], v118 offset:45568
	s_waitcnt lgkmcnt(0)
	v_mfma_f32_16x16x32_f16 v[36:39], v[36:39], v[24:27], v[44:47]
	s_nop 2
	ds_read_b128 v[44:47], v118 offset:62464
	v_mfma_f32_16x16x32_f16 v[40:43], v[40:43], v[24:27], v[48:51]
	s_waitcnt lgkmcnt(0)
	v_mfma_f32_16x16x32_f16 v[24:27], v[44:47], v[24:27], v[32:35]
	s_nop 2
	v_add_f32_e32 v32, v53, v52
	v_add_f32_e32 v32, v54, v32
	v_add_f32_e32 v32, v55, v32
	v_add_f32_e32 v32, v56, v32
	v_sub_f32_e32 v20, v20, v119
	v_mul_f32_e32 v20, 0x3fb8aa3b, v20
	v_sub_f32_e32 v21, v21, v119
	v_sub_f32_e32 v16, v16, v119
	v_exp_f32_e32 v20, v20
	v_mul_f32_e32 v21, 0x3fb8aa3b, v21
	v_sub_f32_e32 v22, v22, v119
	v_mul_f32_e32 v16, 0x3fb8aa3b, v16
	v_exp_f32_e32 v21, v21
	v_mul_f32_e32 v22, 0x3fb8aa3b, v22
	v_sub_f32_e32 v23, v23, v119
	v_exp_f32_e32 v45, v16
	v_sub_f32_e32 v16, v17, v119
	v_exp_f32_e32 v22, v22
	v_mul_f32_e32 v23, 0x3fb8aa3b, v23
	v_mul_f32_e32 v16, 0x3fb8aa3b, v16
	v_exp_f32_e32 v23, v23
	v_exp_f32_e32 v46, v16
	v_sub_f32_e32 v16, v18, v119
	v_add_f32_e32 v32, v20, v32
	v_mul_f32_e32 v16, 0x3fb8aa3b, v16
	v_add_f32_e32 v32, v21, v32
	v_exp_f32_e32 v47, v16
	v_sub_f32_e32 v16, v19, v119
	v_add_f32_e32 v32, v22, v32
	v_mul_f32_e32 v16, 0x3fb8aa3b, v16
	v_add_f32_e32 v44, v23, v32
	v_exp_f32_e32 v48, v16
	v_cvt_pk_f16_f32 v17, v22, v23
	v_cvt_pk_f16_f32 v16, v20, v21
	ds_read_b128 v[20:23], v118 offset:37184
	v_cvt_pk_f16_f32 v19, v47, v48
	v_cvt_pk_f16_f32 v18, v45, v46
	ds_read_b128 v[32:35], v118 offset:54080
	s_waitcnt lgkmcnt(1)
	v_mfma_f32_16x16x32_f16 v[20:23], v[20:23], v[16:19], v[28:31]
	s_nop 2
	ds_read_b128 v[28:31], v118 offset:45632
	s_waitcnt lgkmcnt(0)
	v_mfma_f32_16x16x32_f16 v[28:31], v[28:31], v[16:19], v[36:39]
	s_nop 2
	ds_read_b128 v[36:39], v118 offset:62528
	v_mfma_f32_16x16x32_f16 v[32:35], v[32:35], v[16:19], v[40:43]
	s_waitcnt lgkmcnt(0)
	v_mfma_f32_16x16x32_f16 v[16:19], v[36:39], v[16:19], v[24:27]
	s_nop 2
	v_add_f32_e32 v24, v45, v44
	v_add_f32_e32 v24, v46, v24
	v_add_f32_e32 v24, v47, v24
	v_add_f32_e32 v24, v48, v24
	v_sub_f32_e32 v12, v12, v119
	v_mul_f32_e32 v12, 0x3fb8aa3b, v12
	v_sub_f32_e32 v13, v13, v119
	v_sub_f32_e32 v8, v8, v119
	v_exp_f32_e32 v12, v12
	v_mul_f32_e32 v13, 0x3fb8aa3b, v13
	v_sub_f32_e32 v14, v14, v119
	v_mul_f32_e32 v8, 0x3fb8aa3b, v8
	v_exp_f32_e32 v13, v13
	v_mul_f32_e32 v14, 0x3fb8aa3b, v14
	v_sub_f32_e32 v15, v15, v119
	v_exp_f32_e32 v37, v8
	v_sub_f32_e32 v8, v9, v119
	v_exp_f32_e32 v14, v14
	v_mul_f32_e32 v15, 0x3fb8aa3b, v15
	v_mul_f32_e32 v8, 0x3fb8aa3b, v8
	v_exp_f32_e32 v15, v15
	v_exp_f32_e32 v38, v8
	v_sub_f32_e32 v8, v10, v119
	v_add_f32_e32 v24, v12, v24
	v_mul_f32_e32 v8, 0x3fb8aa3b, v8
	v_add_f32_e32 v24, v13, v24
	v_exp_f32_e32 v39, v8
	v_sub_f32_e32 v8, v11, v119
	v_add_f32_e32 v24, v14, v24
	v_mul_f32_e32 v8, 0x3fb8aa3b, v8
	v_add_f32_e32 v36, v15, v24
	v_exp_f32_e32 v40, v8
	v_cvt_pk_f16_f32 v9, v14, v15
	v_cvt_pk_f16_f32 v8, v12, v13
	ds_read_b128 v[12:15], v118 offset:37248
	v_cvt_pk_f16_f32 v11, v39, v40
	v_cvt_pk_f16_f32 v10, v37, v38
	ds_read_b128 v[24:27], v118 offset:54144
	s_waitcnt lgkmcnt(1)
	v_mfma_f32_16x16x32_f16 v[12:15], v[12:15], v[8:11], v[20:23]
	s_nop 2
	ds_read_b128 v[20:23], v118 offset:45696
	s_waitcnt lgkmcnt(0)
	v_mfma_f32_16x16x32_f16 v[20:23], v[20:23], v[8:11], v[28:31]
	s_nop 2
	ds_read_b128 v[28:31], v118 offset:62592
	v_mfma_f32_16x16x32_f16 v[24:27], v[24:27], v[8:11], v[32:35]
	s_waitcnt lgkmcnt(0)
; template <bool CL>
; __device__ __forceinline__ void natten_wave(const Params& p, int l, bool local, int b, int hh, int qrow0  ,
;                             int r, int ct, const f16* lK, const f16* lV) {
;     ...
;   sum += __shfl_xor(sum, 16, 64);
;   sum += __shfl_xor(sum, 32, 64);
;   float inv = 1.0f / sum;
; #pragma unroll
;   for (int nb = 0; nb < 4; ++nb) {
;     f16x4 ov;
;     ov[0] = (f16)(o[nb][0] * inv);
;     ov[1] = (f16)(o[nb][1] * inv);
;     ov[2] = (f16)(o[nb][2] * inv);
;     ov[3] = (f16)(o[nb][3] * inv);
;     *(f16x4*)(br + (size_t)(qrow0 + lq) * DM + 640 + hh * HD + nb * 16 + 4 * g) = ov;
;   }
	v_mfma_f32_16x16x32_f16 v[8:11], v[28:31], v[8:11], v[16:19]
	s_nop 2
	v_add_f32_e32 v16, v37, v36
	v_add_f32_e32 v16, v38, v16
	v_add_f32_e32 v16, v39, v16
	v_add_f32_e32 v16, v40, v16
	v_sub_f32_e32 v4, v4, v119
	v_mul_f32_e32 v4, 0x3fb8aa3b, v4
	v_sub_f32_e32 v5, v5, v119
	v_sub_f32_e32 v0, v0, v119
	v_exp_f32_e32 v4, v4
	v_mul_f32_e32 v5, 0x3fb8aa3b, v5
	v_sub_f32_e32 v6, v6, v119
	v_mul_f32_e32 v0, 0x3fb8aa3b, v0
	v_exp_f32_e32 v5, v5
	v_mul_f32_e32 v6, 0x3fb8aa3b, v6
	v_sub_f32_e32 v7, v7, v119
	v_exp_f32_e32 v29, v0
	v_sub_f32_e32 v0, v1, v119
	v_exp_f32_e32 v6, v6
	v_mul_f32_e32 v7, 0x3fb8aa3b, v7
	v_mul_f32_e32 v0, 0x3fb8aa3b, v0
	v_exp_f32_e32 v7, v7
	v_exp_f32_e32 v30, v0
	v_sub_f32_e32 v0, v2, v119
	v_add_f32_e32 v16, v4, v16
	v_mul_f32_e32 v0, 0x3fb8aa3b, v0
	v_add_f32_e32 v16, v5, v16
	v_exp_f32_e32 v31, v0
	v_sub_f32_e32 v0, v3, v119
	v_add_f32_e32 v16, v6, v16
	v_mul_f32_e32 v0, 0x3fb8aa3b, v0
	v_add_f32_e32 v28, v7, v16
	v_exp_f32_e32 v32, v0
	v_cvt_pk_f16_f32 v1, v6, v7
	v_cvt_pk_f16_f32 v0, v4, v5
	ds_read_b128 v[4:7], v118 offset:37312
	v_cvt_pk_f16_f32 v3, v31, v32
	v_cvt_pk_f16_f32 v2, v29, v30
	ds_read_b128 v[16:19], v118 offset:54208
	s_waitcnt lgkmcnt(1)
	v_mfma_f32_16x16x32_f16 v[4:7], v[4:7], v[0:3], v[12:15]
	s_nop 2
	ds_read_b128 v[12:15], v118 offset:45760
	s_waitcnt lgkmcnt(0)
	v_mfma_f32_16x16x32_f16 v[12:15], v[12:15], v[0:3], v[20:23]
	s_nop 2
	ds_read_b128 v[20:23], v118 offset:62656
	v_mfma_f32_16x16x32_f16 v[16:19], v[16:19], v[0:3], v[24:27]
	s_waitcnt lgkmcnt(0)
	v_mfma_f32_16x16x32_f16 v[0:3], v[20:23], v[0:3], v[8:11]
	s_nop 2
	v_add_f32_e32 v8, v29, v28
	v_add_f32_e32 v8, v30, v8
	v_add_f32_e32 v8, v31, v8
	v_add_f32_e32 v8, v32, v8
	ds_bpermute_b32 v9, v109, v8
	v_mov_b32_e32 v107, v165
	s_add_i32 s38, s38, s33
	s_sub_i32 s40, s40, s33
	s_cmpk_lt_i32 s38, 0x100
	s_waitcnt lgkmcnt(0)
	v_add_f32_e32 v8, v8, v9
	ds_bpermute_b32 v9, v110, v8
	s_waitcnt lgkmcnt(0)
	v_add_f32_e32 v8, v8, v9
	v_readlane_b32 s6, v241, 36
	v_rcp_f32_e32 v10, v8
	s_nop 0
	v_mul_f32_e32 v9, 1.0, v10
	v_mov_b32_e32 v8, v9
	v_lshlrev_b64 v[10:11], 11, v[96:97]
	v_lshl_add_u64 v[10:11], v[88:89], 0, v[10:11]
	v_fma_mixlo_f16 v9, v4, v8, 0
	v_mov_b32_e32 v4, v5
	v_mov_b32_e32 v5, v6
	v_lshl_add_u64 v[10:11], s[8:9], 1, v[10:11]
	v_pk_mul_f32 v[4:5], v[4:5], v[8:9] op_sel_hi:[1,0]
	v_lshl_add_u64 v[10:11], v[10:11], 0, v[106:107]
	v_cvt_pk_f16_f32 v5, v4, v5
	v_fma_mixlo_f16 v6, v7, v8, 0
	v_pack_b32_f16 v4, v9, v5
	v_alignbit_b32 v5, v6, v5, 16
	v_add_co_u32_e32 v6, vcc, s70, v10
	v_lshl_add_u64 v[20:21], v[10:11], 0, s[52:53]
	s_nop 0
	v_addc_co_u32_e32 v7, vcc, 0, v11, vcc
	global_store_dwordx2 v[6:7], v[4:5], off offset:1280
	v_mov_b32_e32 v4, v13
	v_mov_b32_e32 v5, v14
	v_pk_mul_f32 v[4:5], v[4:5], v[8:9] op_sel_hi:[1,0]
	v_fma_mixlo_f16 v6, v12, v8, 0
	v_cvt_pk_f16_f32 v5, v4, v5
	v_pack_b32_f16 v4, v6, v5
	v_fma_mixlo_f16 v6, v15, v8, 0
	v_alignbit_b32 v5, v6, v5, 16
	global_store_dwordx2 v[20:21], v[4:5], off offset:32
	v_mov_b32_e32 v4, v17
	v_mov_b32_e32 v5, v18
	v_pk_mul_f32 v[4:5], v[4:5], v[8:9] op_sel_hi:[1,0]
	v_fma_mixlo_f16 v6, v16, v8, 0
	v_cvt_pk_f16_f32 v5, v4, v5
	v_pack_b32_f16 v4, v6, v5
	v_fma_mixlo_f16 v6, v19, v8, 0
	v_alignbit_b32 v5, v6, v5, 16
	global_store_dwordx2 v[20:21], v[4:5], off offset:64
	v_fma_mixlo_f16 v4, v0, v8, 0
	v_mov_b32_e32 v0, v1
	v_mov_b32_e32 v1, v2
	v_pk_mul_f32 v[0:1], v[0:1], v[8:9] op_sel_hi:[1,0]
	v_fma_mixlo_f16 v2, v3, v8, 0
	v_cvt_pk_f16_f32 v1, v0, v1
	v_pack_b32_f16 v0, v4, v1
	v_alignbit_b32 v1, v2, v1, 16
	v_add_u32_e32 v96, s6, v96
	global_store_dwordx2 v[20:21], v[0:1], off offset:96
	s_cbranch_scc0 .LBB0_685
